# phase-1 copier blocks stop pulling chunks once 561 of 888 GEMM tiles are done (was: all done), done-counter checked before the first pull
# speedup vs baseline: 1.0301x; 1.0089x over previous
.Lcp1_entry:
	v_readfirstlane_b32 s0, v192
	v_lshlrev_b32_e32 v16, 4, v192
	s_add_u32 s4, s38, 0xc7b7100
	s_addc_u32 s5, s39, 0
	s_add_u32 s6, s38, 0xc7b7200
	s_addc_u32 s7, s39, 0
	s_lshr_b32 s0, s0, 6
	s_mov_b32 s1, 0
	s_mov_b32 s30, 2
	v_mov_b32_e32 v93, 0
	v_mov_b32_e32 v94, 1
	v_mov_b32_e32 v95, 16
	v_mov_b32_e32 v96, 20
	v_add_u32_e32 v17, 0x2000, v16
	v_add_u32_e32 v18, 0x4000, v16
	v_add_u32_e32 v19, 0x6000, v16
	v_add_u32_e32 v20, 0x8000, v16
	v_add_u32_e32 v21, 0xa000, v16
	v_add_u32_e32 v22, 0xc000, v16
	v_add_u32_e32 v23, 0xe000, v16
	v_add_u32_e32 v104, 0x10000, v16
	v_add_u32_e32 v105, 0x12000, v16
	v_add_u32_e32 v106, 0x14000, v16
	v_add_u32_e32 v107, 0x16000, v16
	v_add_u32_e32 v108, 0x18000, v16
	v_add_u32_e32 v109, 0x1a000, v16
	v_add_u32_e32 v110, 0x1c000, v16
	v_add_u32_e32 v111, 0x1e000, v16
	s_barrier
	s_cmp_lg_u32 s0, 0
	s_cbranch_scc1 .Lcp1_p0
	s_mov_b64 s[22:23], exec
	s_mov_b64 exec, 1
	global_load_dword v118, v93, s[6:7] sc1
	v_mov_b32_e32 v117, 0xa80
	s_waitcnt vmcnt(0)
	v_readfirstlane_b32 s25, v118
	s_cmpk_gt_u32 s25, 0x230
	s_cbranch_scc1 .Lcp1_pnone
	v_mov_b32_e32 v117, 2
	global_atomic_add v117, v93, v117, s[4:5] sc0
	s_waitcnt vmcnt(0)
.Lcp1_pnone:
	ds_write_b32 v96, v117
	s_waitcnt lgkmcnt(0)
	s_mov_b64 exec, s[22:23]
.Lcp1_p0:
	s_barrier
	ds_read_b32 v119, v96
	s_waitcnt lgkmcnt(0)
	v_readfirstlane_b32 s16, v119
	s_add_u32 s17, s16, 1
	s_cmpk_ge_u32 s16, 0xa80
	s_cbranch_scc1 .Lcp1_exit
	s_cmpk_lt_u32 s16, 0x800
	s_cbranch_scc1 .Lcp1_ac_pro_g2
	s_cmpk_lt_u32 s16, 0xa00
	s_cbranch_scc1 .Lcp1_ac_pro_g1
	s_sub_u32 s18, s16, 0xa00
	s_mov_b32 s8, s80
	s_mov_b32 s9, s81
	s_mov_b32 s19, 0x4a40000
	s_mov_b32 s24, 0x1c000
	s_branch .Lcp1_ac_pro_j

.Lcp1_ac_A_j:
	s_lshl_b32 s18, s18, 17
	v_add_u32_e32 v92, s24, v16
	s_add_u32 s14, s36, s19
	s_addc_u32 s15, s37, 0
	s_add_u32 s14, s14, s18
	s_addc_u32 s15, s15, 0
	s_add_u32 s12, s12, s18
	s_addc_u32 s13, s13, 0
	s_add_u32 s12, s12, 0x2000
	s_addc_u32 s13, s13, 0
	global_load_dwordx4 v[180:183], v16, s[12:13] nt
	global_load_dwordx4 v[184:187], v17, s[12:13] nt
	global_load_dwordx4 v[188:191], v18, s[12:13] nt
	global_load_dwordx4 v[196:199], v19, s[12:13] nt
	global_load_dwordx4 v[200:203], v20, s[12:13] nt
	global_load_dwordx4 v[204:207], v21, s[12:13] nt
	global_load_dwordx4 v[208:211], v22, s[12:13] nt
	global_load_dwordx4 v[212:215], v23, s[12:13] nt
	global_load_dwordx4 v[216:219], v104, s[12:13] nt
	global_load_dwordx4 v[220:223], v105, s[12:13] nt
	global_load_dwordx4 v[224:227], v106, s[12:13] nt
	global_load_dwordx4 v[228:231], v107, s[12:13] nt
	global_load_dwordx4 v[244:247], v108, s[12:13] nt
	global_load_dwordx4 v[248:251], v109, s[12:13] nt
	global_load_dwordx4 v[4:7], v110, s[12:13] nt
	global_load_dwordx4 v[8:11], v92, s[12:13] nt
	s_waitcnt vmcnt(31)
	global_store_dwordx4 v16, v[30:33], s[10:11] nt
	s_waitcnt vmcnt(31)
	global_store_dwordx4 v17, v[34:37], s[10:11] nt
	s_waitcnt vmcnt(31)
	global_store_dwordx4 v18, v[38:41], s[10:11] nt
	s_waitcnt vmcnt(31)
	global_store_dwordx4 v19, v[42:45], s[10:11] nt
	s_waitcnt vmcnt(31)
	global_store_dwordx4 v20, v[46:49], s[10:11] nt
	s_waitcnt vmcnt(31)
	global_store_dwordx4 v21, v[50:53], s[10:11] nt
	s_waitcnt vmcnt(31)
	global_store_dwordx4 v22, v[54:57], s[10:11] nt
	s_waitcnt vmcnt(31)
	global_store_dwordx4 v23, v[58:61], s[10:11] nt
	s_waitcnt vmcnt(31)
	global_store_dwordx4 v104, v[62:65], s[10:11] nt
	s_waitcnt vmcnt(31)
	global_store_dwordx4 v105, v[66:69], s[10:11] nt
	s_waitcnt vmcnt(31)
	global_store_dwordx4 v106, v[70:73], s[10:11] nt
	s_waitcnt vmcnt(31)
	global_store_dwordx4 v107, v[74:77], s[10:11] nt
	s_waitcnt vmcnt(31)
	global_store_dwordx4 v108, v[164:167], s[10:11] nt
	s_waitcnt vmcnt(31)
	global_store_dwordx4 v109, v[168:171], s[10:11] nt
	s_waitcnt vmcnt(31)
	global_store_dwordx4 v110, v[172:175], s[10:11] nt
	s_waitcnt vmcnt(31)
	global_store_dwordx4 v91, v[176:179], s[10:11] nt
	s_cmp_lg_u32 s0, 0
	s_cbranch_scc1 .Lcp1_A_s4
	s_mov_b64 s[22:23], exec
	s_mov_b64 exec, 1
	s_cmp_lg_u32 s1, 0
	s_cbranch_scc1 .Lcp1_A_s4stop
	s_waitcnt vmcnt(32)
	v_readfirstlane_b32 s25, v118
	s_cmpk_gt_u32 s25, 0x230
	s_cselect_b32 s1, 1, 0
	v_readfirstlane_b32 s26, v117
	s_cmpk_ge_u32 s26, 0xa80
	s_cselect_b32 s27, 1, 0
	s_or_b32 s1, s1, s27
	s_branch .Lcp1_A_s4pub

.Lcp1_ac_B_j:
	s_lshl_b32 s18, s18, 17
	v_add_u32_e32 v91, s24, v16
	s_add_u32 s10, s36, s19
	s_addc_u32 s11, s37, 0
	s_add_u32 s10, s10, s18
	s_addc_u32 s11, s11, 0
	s_add_u32 s8, s8, s18
	s_addc_u32 s9, s9, 0
	s_add_u32 s8, s8, 0x2000
	s_addc_u32 s9, s9, 0
	global_load_dwordx4 v[30:33], v16, s[8:9] nt
	global_load_dwordx4 v[34:37], v17, s[8:9] nt
	global_load_dwordx4 v[38:41], v18, s[8:9] nt
	global_load_dwordx4 v[42:45], v19, s[8:9] nt
	global_load_dwordx4 v[46:49], v20, s[8:9] nt
	global_load_dwordx4 v[50:53], v21, s[8:9] nt
	global_load_dwordx4 v[54:57], v22, s[8:9] nt
	global_load_dwordx4 v[58:61], v23, s[8:9] nt
	global_load_dwordx4 v[62:65], v104, s[8:9] nt
	global_load_dwordx4 v[66:69], v105, s[8:9] nt
	global_load_dwordx4 v[70:73], v106, s[8:9] nt
	global_load_dwordx4 v[74:77], v107, s[8:9] nt
	global_load_dwordx4 v[164:167], v108, s[8:9] nt
	global_load_dwordx4 v[168:171], v109, s[8:9] nt
	global_load_dwordx4 v[172:175], v110, s[8:9] nt
	global_load_dwordx4 v[176:179], v91, s[8:9] nt
	s_waitcnt vmcnt(31)
	global_store_dwordx4 v16, v[180:183], s[14:15] nt
	s_waitcnt vmcnt(31)
	global_store_dwordx4 v17, v[184:187], s[14:15] nt
	s_waitcnt vmcnt(31)
	global_store_dwordx4 v18, v[188:191], s[14:15] nt
	s_waitcnt vmcnt(31)
	global_store_dwordx4 v19, v[196:199], s[14:15] nt
	s_waitcnt vmcnt(31)
	global_store_dwordx4 v20, v[200:203], s[14:15] nt
	s_waitcnt vmcnt(31)
	global_store_dwordx4 v21, v[204:207], s[14:15] nt
	s_waitcnt vmcnt(31)
	global_store_dwordx4 v22, v[208:211], s[14:15] nt
	s_waitcnt vmcnt(31)
	global_store_dwordx4 v23, v[212:215], s[14:15] nt
	s_waitcnt vmcnt(31)
	global_store_dwordx4 v104, v[216:219], s[14:15] nt
	s_waitcnt vmcnt(31)
	global_store_dwordx4 v105, v[220:223], s[14:15] nt
	s_waitcnt vmcnt(31)
	global_store_dwordx4 v106, v[224:227], s[14:15] nt
	s_waitcnt vmcnt(31)
	global_store_dwordx4 v107, v[228:231], s[14:15] nt
	s_waitcnt vmcnt(31)
	global_store_dwordx4 v108, v[244:247], s[14:15] nt
	s_waitcnt vmcnt(31)
	global_store_dwordx4 v109, v[248:251], s[14:15] nt
	s_waitcnt vmcnt(31)
	global_store_dwordx4 v110, v[4:7], s[14:15] nt
	s_waitcnt vmcnt(31)
	global_store_dwordx4 v92, v[8:11], s[14:15] nt
	s_cmp_lg_u32 s0, 0
	s_cbranch_scc1 .Lcp1_B_s4
	s_mov_b64 s[22:23], exec
	s_mov_b64 exec, 1
	s_cmp_lg_u32 s1, 0
	s_cbranch_scc1 .Lcp1_B_s4stop
	s_waitcnt vmcnt(32)
	v_readfirstlane_b32 s25, v118
	s_cmpk_gt_u32 s25, 0x230
	s_cselect_b32 s1, 1, 0
	v_readfirstlane_b32 s26, v117
	s_cmpk_ge_u32 s26, 0xa80
	s_cselect_b32 s27, 1, 0
	s_or_b32 s1, s1, s27
	s_branch .Lcp1_B_s4pub

.LBB0_1193:
.Lcpd_entry:
	v_readfirstlane_b32 s0, v192
	v_lshlrev_b32_e32 v16, 4, v192
	s_add_u32 s4, s38, 0xc7b7100
	s_addc_u32 s5, s39, 0
	s_add_u32 s6, s38, 0xc7b7200
	s_addc_u32 s7, s39, 0
	s_lshr_b32 s0, s0, 6
	s_mov_b32 s1, 0
	s_mov_b32 s30, 2
	v_mov_b32_e32 v93, 0
	v_mov_b32_e32 v94, 1
	v_mov_b32_e32 v95, 16
	v_mov_b32_e32 v96, 20
	v_add_u32_e32 v17, 0x2000, v16
	v_add_u32_e32 v18, 0x4000, v16
	v_add_u32_e32 v19, 0x6000, v16
	v_add_u32_e32 v20, 0x8000, v16
	v_add_u32_e32 v21, 0xa000, v16
	v_add_u32_e32 v22, 0xc000, v16
	v_add_u32_e32 v23, 0xe000, v16
	v_add_u32_e32 v104, 0x10000, v16
	v_add_u32_e32 v105, 0x12000, v16
	v_add_u32_e32 v106, 0x14000, v16
	v_add_u32_e32 v107, 0x16000, v16
	v_add_u32_e32 v108, 0x18000, v16
	v_add_u32_e32 v109, 0x1a000, v16
	v_add_u32_e32 v110, 0x1c000, v16
	v_add_u32_e32 v111, 0x1e000, v16
	s_barrier
	s_cmp_lg_u32 s0, 0
	s_cbranch_scc1 .Lcpd_p0
	s_mov_b64 s[22:23], exec
	s_mov_b64 exec, 1
	v_mov_b32_e32 v117, 2
	global_atomic_add v117, v93, v117, s[4:5] sc0
	s_waitcnt vmcnt(0)
	ds_write_b32 v96, v117
	s_waitcnt lgkmcnt(0)
	s_mov_b64 exec, s[22:23]
